# hand-scheduled software-pipelined k-loop for FFN-up GEMM (phases 5,12), 2 staging sets
# speedup vs baseline: 1.0312x; 1.0312x over previous
.LBB0_669:
	s_or_b64 exec, exec, s[18:19]
	v_add_co_u32_e32 v4, vcc, 0x7000, v30
	s_mul_i32 s18, s52, 62
	s_nop 0
	v_addc_co_u32_e32 v5, vcc, 0, v31, vcc
	global_load_dwordx4 v[110:113], v[4:5], off
	v_ashrrev_i32_e32 v4, 3, v41
	s_add_i32 s18, s3, s18
	v_lshrrev_b32_e32 v116, 4, v4
	s_add_i32 s18, s18, s51
	v_ashrrev_i32_e32 v8, 3, v40
	v_lshlrev_b64 v[4:5], 18, v[116:117]
	s_lshl_b32 s18, s18, 1
	v_lshl_add_u64 v[2:3], v[2:3], 1, v[4:5]
	v_lshrrev_b32_e32 v116, 4, v8
	v_subrev_u16_e32 v4, s18, v163
	v_ashrrev_i32_e32 v7, 3, v39
	v_lshl_add_u64 v[128:129], v[122:123], 0, v[2:3]
	v_lshlrev_b64 v[2:3], 18, v[116:117]
	v_and_b32_e32 v4, 0x7f, v4
	s_waitcnt lgkmcnt(0)
	s_barrier
	ds_read_b128 v[102:105], v168 offset:18432
	ds_read_b128 v[94:97], v168 offset:23040
	ds_read_b128 v[106:109], v169
	ds_read_b128 v[98:101], v169 offset:4608
	v_lshl_or_b32 v2, v4, 7, v2
	v_lshrrev_b32_e32 v116, 4, v7
	v_subrev_u16_e32 v4, s18, v164
	v_ashrrev_i32_e32 v6, 3, v38
	v_lshl_add_u64 v[130:131], v[122:123], 0, v[2:3]
	v_lshlrev_b64 v[2:3], 18, v[116:117]
	v_and_b32_e32 v4, 0x7f, v4
	v_lshl_or_b32 v2, v4, 7, v2
	v_lshrrev_b32_e32 v116, 4, v6
	v_subrev_u16_e32 v4, s18, v165
	v_lshl_add_u64 v[132:133], v[122:123], 0, v[2:3]
	v_lshlrev_b64 v[2:3], 18, v[116:117]
	v_and_b32_e32 v4, 0x7f, v4
	v_lshl_or_b32 v2, v4, 7, v2
	v_lshl_add_u64 v[134:135], v[122:123], 0, v[2:3]
	v_mov_b32_e32 v2, 0
	s_mov_b32 s15, 0
	v_lshl_add_u64 v[136:137], v[124:125], 0, s[16:17]
	s_mov_b64 s[16:17], 0
	v_mov_b32_e32 v3, v2
	v_mov_b32_e32 v4, v2
	v_mov_b32_e32 v5, v2
	v_mov_b32_e32 v6, v2
	v_mov_b32_e32 v7, v2
	v_mov_b32_e32 v8, v2
	v_mov_b32_e32 v9, v2
	v_mov_b32_e32 v10, v2
	v_mov_b32_e32 v11, v2
	v_mov_b32_e32 v12, v2
	v_mov_b32_e32 v13, v2
	v_mov_b32_e32 v14, v2
	v_mov_b32_e32 v15, v2
	v_mov_b32_e32 v16, v2
	v_mov_b32_e32 v17, v2
	v_mov_b32_e32 v18, v2
	v_mov_b32_e32 v19, v2
	v_mov_b32_e32 v20, v2
	v_mov_b32_e32 v21, v2
	v_mov_b32_e32 v22, v2
	v_mov_b32_e32 v23, v2
	v_mov_b32_e32 v24, v2
	v_mov_b32_e32 v25, v2
	v_mov_b32_e32 v26, v2
	v_mov_b32_e32 v27, v2
	v_mov_b32_e32 v28, v2
	v_mov_b32_e32 v29, v2
	v_mov_b32_e32 v30, v2
	v_mov_b32_e32 v31, v2
	v_mov_b32_e32 v32, v2
	v_mov_b32_e32 v33, v2
	v_mov_b32_e32 v34, v2
	v_mov_b32_e32 v35, v2
	v_mov_b32_e32 v36, v2
	v_mov_b32_e32 v37, v2
	v_mov_b32_e32 v38, v2
	v_mov_b32_e32 v39, v2
	v_mov_b32_e32 v40, v2
	v_mov_b32_e32 v41, v2
	v_mov_b32_e32 v42, v2
	v_mov_b32_e32 v43, v2
	v_mov_b32_e32 v44, v2
	v_mov_b32_e32 v45, v2
	v_mov_b32_e32 v46, v2
	v_mov_b32_e32 v47, v2
	v_mov_b32_e32 v48, v2
	v_mov_b32_e32 v49, v2
	v_mov_b32_e32 v50, v2
	v_mov_b32_e32 v51, v2
	v_mov_b32_e32 v52, v2
	v_mov_b32_e32 v53, v2
	v_mov_b32_e32 v54, v2
	v_mov_b32_e32 v55, v2
	v_mov_b32_e32 v56, v2
	v_mov_b32_e32 v57, v2
	v_mov_b32_e32 v58, v2
	v_mov_b32_e32 v59, v2
	v_mov_b32_e32 v60, v2
	v_mov_b32_e32 v61, v2
	v_mov_b32_e32 v62, v2
	v_mov_b32_e32 v63, v2
	v_mov_b32_e32 v64, v2
	v_mov_b32_e32 v65, v2
	s_mov_b32 s63, 0
	s_mov_b32 s62, 0x102c000
	v_lshl_add_u64 v[220:221], v[136:137], 0, s[62:63]
	s_mov_b32 s62, 0x102d000
	v_lshl_add_u64 v[222:223], v[136:137], 0, s[62:63]
	s_mov_b32 s62, 0x102e000
	v_lshl_add_u64 v[224:225], v[136:137], 0, s[62:63]
	s_mov_b32 s62, 0x102f000
	v_lshl_add_u64 v[226:227], v[136:137], 0, s[62:63]
	v_mov_b32_e32 v188, 0
	v_mov_b32_e32 v189, 0
	v_mov_b32_e32 v190, 0
	v_mov_b32_e32 v191, 0
	v_mov_b32_e32 v196, 0
	v_mov_b32_e32 v197, 0
	v_mov_b32_e32 v198, 0
	v_mov_b32_e32 v199, 0
	v_mov_b32_e32 v204, 0
	v_mov_b32_e32 v205, 0
	v_mov_b32_e32 v206, 0
	v_mov_b32_e32 v207, 0
	v_mov_b32_e32 v212, 0
	v_mov_b32_e32 v213, 0
	v_mov_b32_e32 v214, 0
	v_mov_b32_e32 v215, 0
	s_mov_b64 exec, s[4:5]
	global_load_dwordx4 v[188:191], v[134:135], off
	s_mov_b64 exec, -1
	global_load_dwordx4 v[192:195], v[220:221], off
	s_mov_b64 exec, s[6:7]
	global_load_dwordx4 v[196:199], v[132:133], off
	s_mov_b64 exec, -1
	global_load_dwordx4 v[200:203], v[222:223], off
	s_mov_b64 exec, s[8:9]
	global_load_dwordx4 v[204:207], v[130:131], off
	s_mov_b64 exec, -1
	global_load_dwordx4 v[208:211], v[224:225], off
	s_mov_b64 exec, s[10:11]
	global_load_dwordx4 v[212:215], v[128:129], off
	s_mov_b64 exec, -1
	global_load_dwordx4 v[216:219], v[226:227], off
	s_mov_b32 s64, 0x4000
	s_mov_b32 s65, 0
	s_mov_b32 s66, 6
.Lk5_loop:
	ds_read_b128 v[172:175], v168 offset:18464
	ds_read_b128 v[176:179], v168 offset:23072
	ds_read_b128 v[180:183], v169 offset:32
	ds_read_b128 v[184:187], v169 offset:4640
	s_waitcnt lgkmcnt(4)
	v_mfma_f32_32x32x16_bf16 v[50:65], v[102:105], v[106:109], v[50:65]
	s_waitcnt vmcnt(15)
	ds_write_b128 v140, v[66:69] offset:36864
	v_mfma_f32_32x32x16_bf16 v[34:49], v[94:97], v[106:109], v[34:49]
	s_waitcnt vmcnt(14)
	ds_write_b128 v140, v[74:77] offset:55296
	v_mfma_f32_32x32x16_bf16 v[18:33], v[102:105], v[98:101], v[18:33]
	s_waitcnt vmcnt(13)
	ds_write_b128 v142, v[70:73] offset:36864
	v_mfma_f32_32x32x16_bf16 v[2:17], v[94:97], v[98:101], v[2:17]
	s_waitcnt vmcnt(12)
	ds_write_b128 v142, v[82:85] offset:55296
	ds_read_b128 v[102:105], v168 offset:18496
	ds_read_b128 v[94:97], v168 offset:23104
	ds_read_b128 v[106:109], v169 offset:64
	ds_read_b128 v[98:101], v169 offset:4672
	s_waitcnt lgkmcnt(4)
	v_mfma_f32_32x32x16_bf16 v[50:65], v[172:175], v[180:183], v[50:65]
	s_waitcnt vmcnt(11)
	ds_write_b128 v144, v[78:81] offset:36864
	v_mfma_f32_32x32x16_bf16 v[34:49], v[176:179], v[180:183], v[34:49]
	s_waitcnt vmcnt(10)
	ds_write_b128 v144, v[86:89] offset:55296
	v_mfma_f32_32x32x16_bf16 v[18:33], v[172:175], v[184:187], v[18:33]
	s_waitcnt vmcnt(9)
	ds_write_b128 v146, v[90:93] offset:36864
	v_mfma_f32_32x32x16_bf16 v[2:17], v[176:179], v[184:187], v[2:17]
	s_waitcnt vmcnt(8)
	ds_write_b128 v146, v[110:113] offset:55296
	ds_read_b128 v[172:175], v168 offset:18528
	ds_read_b128 v[176:179], v168 offset:23136
	ds_read_b128 v[180:183], v169 offset:96
	ds_read_b128 v[184:187], v169 offset:4704
	s_waitcnt lgkmcnt(8)
	v_mfma_f32_32x32x16_bf16 v[50:65], v[102:105], v[106:109], v[50:65]
	s_mov_b64 exec, s[4:5]
	v_lshl_add_u64 v[66:67], v[134:135], 0, s[64:65]
	global_load_dwordx4 v[66:69], v[66:67], off
	s_mov_b64 exec, -1
	v_lshl_add_u64 v[74:75], v[220:221], 0, s[64:65]
	global_load_dwordx4 v[74:77], v[74:75], off
	v_mfma_f32_32x32x16_bf16 v[34:49], v[94:97], v[106:109], v[34:49]
	s_mov_b64 exec, s[6:7]
	v_lshl_add_u64 v[70:71], v[132:133], 0, s[64:65]
	global_load_dwordx4 v[70:73], v[70:71], off
	s_mov_b64 exec, -1
	v_lshl_add_u64 v[82:83], v[222:223], 0, s[64:65]
	global_load_dwordx4 v[82:85], v[82:83], off
	v_mfma_f32_32x32x16_bf16 v[18:33], v[102:105], v[98:101], v[18:33]
	s_mov_b64 exec, s[8:9]
	v_lshl_add_u64 v[78:79], v[130:131], 0, s[64:65]
	global_load_dwordx4 v[78:81], v[78:79], off
	s_mov_b64 exec, -1
	v_lshl_add_u64 v[86:87], v[224:225], 0, s[64:65]
	global_load_dwordx4 v[86:89], v[86:87], off
	v_mfma_f32_32x32x16_bf16 v[2:17], v[94:97], v[98:101], v[2:17]
	s_mov_b64 exec, s[10:11]
	v_lshl_add_u64 v[90:91], v[128:129], 0, s[64:65]
	global_load_dwordx4 v[90:93], v[90:91], off
	s_mov_b64 exec, -1
	v_lshl_add_u64 v[110:111], v[226:227], 0, s[64:65]
	global_load_dwordx4 v[110:113], v[110:111], off
	s_add_u32 s64, s64, 0x4000
	s_addc_u32 s65, s65, 0
	s_waitcnt lgkmcnt(0)
	s_barrier
	ds_read_b128 v[102:105], v168 offset:55296
	ds_read_b128 v[94:97], v168 offset:59904
	ds_read_b128 v[106:109], v169 offset:36864
	ds_read_b128 v[98:101], v169 offset:41472
	v_mfma_f32_32x32x16_bf16 v[50:65], v[172:175], v[180:183], v[50:65]
	v_mfma_f32_32x32x16_bf16 v[34:49], v[176:179], v[180:183], v[34:49]
	v_mfma_f32_32x32x16_bf16 v[18:33], v[172:175], v[184:187], v[18:33]
	v_mfma_f32_32x32x16_bf16 v[2:17], v[176:179], v[184:187], v[2:17]
	ds_read_b128 v[172:175], v168 offset:55328
	ds_read_b128 v[176:179], v168 offset:59936
	ds_read_b128 v[180:183], v169 offset:36896
	ds_read_b128 v[184:187], v169 offset:41504
	s_waitcnt lgkmcnt(4)
	v_mfma_f32_32x32x16_bf16 v[50:65], v[102:105], v[106:109], v[50:65]
	s_waitcnt vmcnt(15)
	ds_write_b128 v140, v[188:191]
	v_mfma_f32_32x32x16_bf16 v[34:49], v[94:97], v[106:109], v[34:49]
	s_waitcnt vmcnt(14)
	ds_write_b128 v140, v[192:195] offset:18432
	v_mfma_f32_32x32x16_bf16 v[18:33], v[102:105], v[98:101], v[18:33]
	s_waitcnt vmcnt(13)
	ds_write_b128 v142, v[196:199]
	v_mfma_f32_32x32x16_bf16 v[2:17], v[94:97], v[98:101], v[2:17]
	s_waitcnt vmcnt(12)
	ds_write_b128 v142, v[200:203] offset:18432
	ds_read_b128 v[102:105], v168 offset:55360
	ds_read_b128 v[94:97], v168 offset:59968
	ds_read_b128 v[106:109], v169 offset:36928
	ds_read_b128 v[98:101], v169 offset:41536
	s_waitcnt lgkmcnt(4)
	v_mfma_f32_32x32x16_bf16 v[50:65], v[172:175], v[180:183], v[50:65]
	s_waitcnt vmcnt(11)
	ds_write_b128 v144, v[204:207]
	v_mfma_f32_32x32x16_bf16 v[34:49], v[176:179], v[180:183], v[34:49]
	s_waitcnt vmcnt(10)
	ds_write_b128 v144, v[208:211] offset:18432
	v_mfma_f32_32x32x16_bf16 v[18:33], v[172:175], v[184:187], v[18:33]
	s_waitcnt vmcnt(9)
	ds_write_b128 v146, v[212:215]
	v_mfma_f32_32x32x16_bf16 v[2:17], v[176:179], v[184:187], v[2:17]
	s_waitcnt vmcnt(8)
	ds_write_b128 v146, v[216:219] offset:18432
	ds_read_b128 v[172:175], v168 offset:55392
	ds_read_b128 v[176:179], v168 offset:60000
	ds_read_b128 v[180:183], v169 offset:36960
	ds_read_b128 v[184:187], v169 offset:41568
	s_waitcnt lgkmcnt(8)
	v_mfma_f32_32x32x16_bf16 v[50:65], v[102:105], v[106:109], v[50:65]
	s_mov_b64 exec, s[4:5]
	v_lshl_add_u64 v[188:189], v[134:135], 0, s[64:65]
	global_load_dwordx4 v[188:191], v[188:189], off
	s_mov_b64 exec, -1
	v_lshl_add_u64 v[192:193], v[220:221], 0, s[64:65]
	global_load_dwordx4 v[192:195], v[192:193], off
	v_mfma_f32_32x32x16_bf16 v[34:49], v[94:97], v[106:109], v[34:49]
	s_mov_b64 exec, s[6:7]
	v_lshl_add_u64 v[196:197], v[132:133], 0, s[64:65]
	global_load_dwordx4 v[196:199], v[196:197], off
	s_mov_b64 exec, -1
	v_lshl_add_u64 v[200:201], v[222:223], 0, s[64:65]
	global_load_dwordx4 v[200:203], v[200:201], off
	v_mfma_f32_32x32x16_bf16 v[18:33], v[102:105], v[98:101], v[18:33]
	s_mov_b64 exec, s[8:9]
	v_lshl_add_u64 v[204:205], v[130:131], 0, s[64:65]
	global_load_dwordx4 v[204:207], v[204:205], off
	s_mov_b64 exec, -1
	v_lshl_add_u64 v[208:209], v[224:225], 0, s[64:65]
	global_load_dwordx4 v[208:211], v[208:209], off
	v_mfma_f32_32x32x16_bf16 v[2:17], v[94:97], v[98:101], v[2:17]
	s_mov_b64 exec, s[10:11]
	v_lshl_add_u64 v[212:213], v[128:129], 0, s[64:65]
	global_load_dwordx4 v[212:215], v[212:213], off
	s_mov_b64 exec, -1
	v_lshl_add_u64 v[216:217], v[226:227], 0, s[64:65]
	global_load_dwordx4 v[216:219], v[216:217], off
	s_add_u32 s64, s64, 0x4000
	s_addc_u32 s65, s65, 0
	s_waitcnt lgkmcnt(0)
	s_barrier
	ds_read_b128 v[102:105], v168 offset:18432
	ds_read_b128 v[94:97], v168 offset:23040
	ds_read_b128 v[106:109], v169
	ds_read_b128 v[98:101], v169 offset:4608
	v_mfma_f32_32x32x16_bf16 v[50:65], v[172:175], v[180:183], v[50:65]
	v_mfma_f32_32x32x16_bf16 v[34:49], v[176:179], v[180:183], v[34:49]
	v_mfma_f32_32x32x16_bf16 v[18:33], v[172:175], v[184:187], v[18:33]
	v_mfma_f32_32x32x16_bf16 v[2:17], v[176:179], v[184:187], v[2:17]
	s_sub_u32 s66, s66, 1
	s_cmp_lg_u32 s66, 0
	s_cbranch_scc1 .Lk5_loop
	ds_read_b128 v[172:175], v168 offset:18464
	ds_read_b128 v[176:179], v168 offset:23072
	ds_read_b128 v[180:183], v169 offset:32
	ds_read_b128 v[184:187], v169 offset:4640
	s_waitcnt lgkmcnt(4)
	v_mfma_f32_32x32x16_bf16 v[50:65], v[102:105], v[106:109], v[50:65]
	s_waitcnt vmcnt(15)
	ds_write_b128 v140, v[66:69] offset:36864
	v_mfma_f32_32x32x16_bf16 v[34:49], v[94:97], v[106:109], v[34:49]
	s_waitcnt vmcnt(14)
	ds_write_b128 v140, v[74:77] offset:55296
	v_mfma_f32_32x32x16_bf16 v[18:33], v[102:105], v[98:101], v[18:33]
	s_waitcnt vmcnt(13)
	ds_write_b128 v142, v[70:73] offset:36864
	v_mfma_f32_32x32x16_bf16 v[2:17], v[94:97], v[98:101], v[2:17]
	s_waitcnt vmcnt(12)
	ds_write_b128 v142, v[82:85] offset:55296
	ds_read_b128 v[102:105], v168 offset:18496
	ds_read_b128 v[94:97], v168 offset:23104
	ds_read_b128 v[106:109], v169 offset:64
	ds_read_b128 v[98:101], v169 offset:4672
	s_waitcnt lgkmcnt(4)
	v_mfma_f32_32x32x16_bf16 v[50:65], v[172:175], v[180:183], v[50:65]
	s_waitcnt vmcnt(11)
	ds_write_b128 v144, v[78:81] offset:36864
	v_mfma_f32_32x32x16_bf16 v[34:49], v[176:179], v[180:183], v[34:49]
	s_waitcnt vmcnt(10)
	ds_write_b128 v144, v[86:89] offset:55296
	v_mfma_f32_32x32x16_bf16 v[18:33], v[172:175], v[184:187], v[18:33]
	s_waitcnt vmcnt(9)
	ds_write_b128 v146, v[90:93] offset:36864
	v_mfma_f32_32x32x16_bf16 v[2:17], v[176:179], v[184:187], v[2:17]
	s_waitcnt vmcnt(8)
	ds_write_b128 v146, v[110:113] offset:55296
	ds_read_b128 v[172:175], v168 offset:18528
	ds_read_b128 v[176:179], v168 offset:23136
	ds_read_b128 v[180:183], v169 offset:96
	ds_read_b128 v[184:187], v169 offset:4704
	s_waitcnt lgkmcnt(8)
	v_mfma_f32_32x32x16_bf16 v[50:65], v[102:105], v[106:109], v[50:65]
	s_mov_b64 exec, s[4:5]
	v_lshl_add_u64 v[66:67], v[134:135], 0, s[64:65]
	global_load_dwordx4 v[66:69], v[66:67], off
	s_mov_b64 exec, -1
	v_lshl_add_u64 v[74:75], v[220:221], 0, s[64:65]
	global_load_dwordx4 v[74:77], v[74:75], off
	v_mfma_f32_32x32x16_bf16 v[34:49], v[94:97], v[106:109], v[34:49]
	s_mov_b64 exec, s[6:7]
	v_lshl_add_u64 v[70:71], v[132:133], 0, s[64:65]
	global_load_dwordx4 v[70:73], v[70:71], off
	s_mov_b64 exec, -1
	v_lshl_add_u64 v[82:83], v[222:223], 0, s[64:65]
	global_load_dwordx4 v[82:85], v[82:83], off
	v_mfma_f32_32x32x16_bf16 v[18:33], v[102:105], v[98:101], v[18:33]
	s_mov_b64 exec, s[8:9]
	v_lshl_add_u64 v[78:79], v[130:131], 0, s[64:65]
	global_load_dwordx4 v[78:81], v[78:79], off
	s_mov_b64 exec, -1
	v_lshl_add_u64 v[86:87], v[224:225], 0, s[64:65]
	global_load_dwordx4 v[86:89], v[86:87], off
	v_mfma_f32_32x32x16_bf16 v[2:17], v[94:97], v[98:101], v[2:17]
	s_mov_b64 exec, s[10:11]
	v_lshl_add_u64 v[90:91], v[128:129], 0, s[64:65]
	global_load_dwordx4 v[90:93], v[90:91], off
	s_mov_b64 exec, -1
	v_lshl_add_u64 v[110:111], v[226:227], 0, s[64:65]
	global_load_dwordx4 v[110:113], v[110:111], off
	s_add_u32 s64, s64, 0x4000
	s_addc_u32 s65, s65, 0
	s_waitcnt lgkmcnt(0)
	s_barrier
	ds_read_b128 v[102:105], v168 offset:55296
	ds_read_b128 v[94:97], v168 offset:59904
	ds_read_b128 v[106:109], v169 offset:36864
	ds_read_b128 v[98:101], v169 offset:41472
	v_mfma_f32_32x32x16_bf16 v[50:65], v[172:175], v[180:183], v[50:65]
	v_mfma_f32_32x32x16_bf16 v[34:49], v[176:179], v[180:183], v[34:49]
	v_mfma_f32_32x32x16_bf16 v[18:33], v[172:175], v[184:187], v[18:33]
	v_mfma_f32_32x32x16_bf16 v[2:17], v[176:179], v[184:187], v[2:17]
	ds_read_b128 v[172:175], v168 offset:55328
	ds_read_b128 v[176:179], v168 offset:59936
	ds_read_b128 v[180:183], v169 offset:36896
	ds_read_b128 v[184:187], v169 offset:41504
	s_waitcnt lgkmcnt(4)
	v_mfma_f32_32x32x16_bf16 v[50:65], v[102:105], v[106:109], v[50:65]
	s_waitcnt vmcnt(15)
	ds_write_b128 v140, v[188:191]
	v_mfma_f32_32x32x16_bf16 v[34:49], v[94:97], v[106:109], v[34:49]
	s_waitcnt vmcnt(14)
	ds_write_b128 v140, v[192:195] offset:18432
	v_mfma_f32_32x32x16_bf16 v[18:33], v[102:105], v[98:101], v[18:33]
	s_waitcnt vmcnt(13)
	ds_write_b128 v142, v[196:199]
	v_mfma_f32_32x32x16_bf16 v[2:17], v[94:97], v[98:101], v[2:17]
	s_waitcnt vmcnt(12)
	ds_write_b128 v142, v[200:203] offset:18432
	ds_read_b128 v[102:105], v168 offset:55360
	ds_read_b128 v[94:97], v168 offset:59968
	ds_read_b128 v[106:109], v169 offset:36928
	ds_read_b128 v[98:101], v169 offset:41536
	s_waitcnt lgkmcnt(4)
	v_mfma_f32_32x32x16_bf16 v[50:65], v[172:175], v[180:183], v[50:65]
	s_waitcnt vmcnt(11)
	ds_write_b128 v144, v[204:207]
	v_mfma_f32_32x32x16_bf16 v[34:49], v[176:179], v[180:183], v[34:49]
	s_waitcnt vmcnt(10)
	ds_write_b128 v144, v[208:211] offset:18432
	v_mfma_f32_32x32x16_bf16 v[18:33], v[172:175], v[184:187], v[18:33]
	s_waitcnt vmcnt(9)
	ds_write_b128 v146, v[212:215]
	v_mfma_f32_32x32x16_bf16 v[2:17], v[176:179], v[184:187], v[2:17]
	s_waitcnt vmcnt(8)
	ds_write_b128 v146, v[216:219] offset:18432
	ds_read_b128 v[172:175], v168 offset:55392
	ds_read_b128 v[176:179], v168 offset:60000
	ds_read_b128 v[180:183], v169 offset:36960
	ds_read_b128 v[184:187], v169 offset:41568
	s_waitcnt lgkmcnt(8)
	v_mfma_f32_32x32x16_bf16 v[50:65], v[102:105], v[106:109], v[50:65]
	v_mfma_f32_32x32x16_bf16 v[34:49], v[94:97], v[106:109], v[34:49]
	v_mfma_f32_32x32x16_bf16 v[18:33], v[102:105], v[98:101], v[18:33]
	v_mfma_f32_32x32x16_bf16 v[2:17], v[94:97], v[98:101], v[2:17]
	s_waitcnt lgkmcnt(0)
	s_barrier
	ds_read_b128 v[102:105], v168 offset:18432
	ds_read_b128 v[94:97], v168 offset:23040
	ds_read_b128 v[106:109], v169
	ds_read_b128 v[98:101], v169 offset:4608
	v_mfma_f32_32x32x16_bf16 v[50:65], v[172:175], v[180:183], v[50:65]
	v_mfma_f32_32x32x16_bf16 v[34:49], v[176:179], v[180:183], v[34:49]
	v_mfma_f32_32x32x16_bf16 v[18:33], v[172:175], v[184:187], v[18:33]
	v_mfma_f32_32x32x16_bf16 v[2:17], v[176:179], v[184:187], v[2:17]
	s_branch .LBB0_679

.LBB0_2386:
	s_or_b64 exec, exec, s[22:23]
	v_add_co_u32_e32 v4, vcc, 0x7000, v30
	s_mul_i32 s22, s38, 62
	s_nop 0
	v_addc_co_u32_e32 v5, vcc, 0, v31, vcc
	global_load_dwordx4 v[110:113], v[4:5], off
	v_ashrrev_i32_e32 v4, 3, v41
	s_add_i32 s22, s24, s22
	v_lshrrev_b32_e32 v116, 4, v4
	s_add_i32 s22, s22, s37
	v_ashrrev_i32_e32 v8, 3, v40
	v_lshlrev_b64 v[4:5], 18, v[116:117]
	s_lshl_b32 s22, s22, 1
	v_lshl_add_u64 v[2:3], v[2:3], 1, v[4:5]
	v_lshrrev_b32_e32 v116, 4, v8
	v_subrev_u16_e32 v4, s22, v163
	v_ashrrev_i32_e32 v7, 3, v39
	v_lshl_add_u64 v[128:129], v[122:123], 0, v[2:3]
	v_lshlrev_b64 v[2:3], 18, v[116:117]
	v_and_b32_e32 v4, 0x7f, v4
	s_waitcnt lgkmcnt(0)
	s_barrier
	ds_read_b128 v[102:105], v168 offset:18432
	ds_read_b128 v[94:97], v168 offset:23040
	ds_read_b128 v[106:109], v169
	ds_read_b128 v[98:101], v169 offset:4608
	v_lshl_or_b32 v2, v4, 7, v2
	v_lshrrev_b32_e32 v116, 4, v7
	v_subrev_u16_e32 v4, s22, v164
	v_ashrrev_i32_e32 v6, 3, v38
	v_lshl_add_u64 v[130:131], v[122:123], 0, v[2:3]
	v_lshlrev_b64 v[2:3], 18, v[116:117]
	v_and_b32_e32 v4, 0x7f, v4
	v_lshl_or_b32 v2, v4, 7, v2
	v_lshrrev_b32_e32 v116, 4, v6
	v_subrev_u16_e32 v4, s22, v165
	v_lshl_add_u64 v[132:133], v[122:123], 0, v[2:3]
	v_lshlrev_b64 v[2:3], 18, v[116:117]
	v_and_b32_e32 v4, 0x7f, v4
	v_lshl_or_b32 v2, v4, 7, v2
	v_lshl_add_u64 v[134:135], v[122:123], 0, v[2:3]
	v_mov_b32_e32 v2, 0
	s_mov_b32 s19, 0
	v_lshl_add_u64 v[136:137], v[124:125], 0, s[20:21]
	s_mov_b64 s[20:21], 0
	v_mov_b32_e32 v3, v2
	v_mov_b32_e32 v4, v2
	v_mov_b32_e32 v5, v2
	v_mov_b32_e32 v6, v2
	v_mov_b32_e32 v7, v2
	v_mov_b32_e32 v8, v2
	v_mov_b32_e32 v9, v2
	v_mov_b32_e32 v10, v2
	v_mov_b32_e32 v11, v2
	v_mov_b32_e32 v12, v2
	v_mov_b32_e32 v13, v2
	v_mov_b32_e32 v14, v2
	v_mov_b32_e32 v15, v2
	v_mov_b32_e32 v16, v2
	v_mov_b32_e32 v17, v2
	v_mov_b32_e32 v18, v2
	v_mov_b32_e32 v19, v2
	v_mov_b32_e32 v20, v2
	v_mov_b32_e32 v21, v2
	v_mov_b32_e32 v22, v2
	v_mov_b32_e32 v23, v2
	v_mov_b32_e32 v24, v2
	v_mov_b32_e32 v25, v2
	v_mov_b32_e32 v26, v2
	v_mov_b32_e32 v27, v2
	v_mov_b32_e32 v28, v2
	v_mov_b32_e32 v29, v2
	v_mov_b32_e32 v30, v2
	v_mov_b32_e32 v31, v2
	v_mov_b32_e32 v32, v2
	v_mov_b32_e32 v33, v2
	v_mov_b32_e32 v34, v2
	v_mov_b32_e32 v35, v2
	v_mov_b32_e32 v36, v2
	v_mov_b32_e32 v37, v2
	v_mov_b32_e32 v38, v2
	v_mov_b32_e32 v39, v2
	v_mov_b32_e32 v40, v2
	v_mov_b32_e32 v41, v2
	v_mov_b32_e32 v42, v2
	v_mov_b32_e32 v43, v2
	v_mov_b32_e32 v44, v2
	v_mov_b32_e32 v45, v2
	v_mov_b32_e32 v46, v2
	v_mov_b32_e32 v47, v2
	v_mov_b32_e32 v48, v2
	v_mov_b32_e32 v49, v2
	v_mov_b32_e32 v50, v2
	v_mov_b32_e32 v51, v2
	v_mov_b32_e32 v52, v2
	v_mov_b32_e32 v53, v2
	v_mov_b32_e32 v54, v2
	v_mov_b32_e32 v55, v2
	v_mov_b32_e32 v56, v2
	v_mov_b32_e32 v57, v2
	v_mov_b32_e32 v58, v2
	v_mov_b32_e32 v59, v2
	v_mov_b32_e32 v60, v2
	v_mov_b32_e32 v61, v2
	v_mov_b32_e32 v62, v2
	v_mov_b32_e32 v63, v2
	v_mov_b32_e32 v64, v2
	v_mov_b32_e32 v65, v2
	s_mov_b32 s63, 0
	s_mov_b32 s62, 0x1b2c000
	v_lshl_add_u64 v[220:221], v[136:137], 0, s[62:63]
	s_mov_b32 s62, 0x1b2d000
	v_lshl_add_u64 v[222:223], v[136:137], 0, s[62:63]
	s_mov_b32 s62, 0x1b2e000
	v_lshl_add_u64 v[224:225], v[136:137], 0, s[62:63]
	s_mov_b32 s62, 0x1b2f000
	v_lshl_add_u64 v[226:227], v[136:137], 0, s[62:63]
	v_mov_b32_e32 v188, 0
	v_mov_b32_e32 v189, 0
	v_mov_b32_e32 v190, 0
	v_mov_b32_e32 v191, 0
	v_mov_b32_e32 v196, 0
	v_mov_b32_e32 v197, 0
	v_mov_b32_e32 v198, 0
	v_mov_b32_e32 v199, 0
	v_mov_b32_e32 v204, 0
	v_mov_b32_e32 v205, 0
	v_mov_b32_e32 v206, 0
	v_mov_b32_e32 v207, 0
	v_mov_b32_e32 v212, 0
	v_mov_b32_e32 v213, 0
	v_mov_b32_e32 v214, 0
	v_mov_b32_e32 v215, 0
	s_mov_b64 exec, s[4:5]
	global_load_dwordx4 v[188:191], v[134:135], off
	s_mov_b64 exec, -1
	global_load_dwordx4 v[192:195], v[220:221], off
	s_mov_b64 exec, s[6:7]
	global_load_dwordx4 v[196:199], v[132:133], off
	s_mov_b64 exec, -1
	global_load_dwordx4 v[200:203], v[222:223], off
	s_mov_b64 exec, s[8:9]
	global_load_dwordx4 v[204:207], v[130:131], off
	s_mov_b64 exec, -1
	global_load_dwordx4 v[208:211], v[224:225], off
	s_mov_b64 exec, s[10:11]
	global_load_dwordx4 v[212:215], v[128:129], off
	s_mov_b64 exec, -1
	global_load_dwordx4 v[216:219], v[226:227], off
	s_mov_b32 s64, 0x4000
	s_mov_b32 s65, 0
	s_mov_b32 s66, 6
